# merge epilogue: merged read-modify-write loads marked nt
# baseline (speedup 1.0000x reference)
.LBB0_1020:
	s_lshl_b32 s13, s20, 8
	s_lshl_b32 s20, s5, 10
	v_mbcnt_lo_u32_b32 v16, -1, 0
	v_mbcnt_hi_u32_b32 v16, -1, v16
	s_lshl_b32 s4, s4, 8
	v_and_or_b32 v176, v16, 15, s45
	s_ashr_i32 s21, s20, 31
	v_ashrrev_i32_e32 v16, 1, v16
	v_add_u32_e32 v168, s13, v176
	s_or_b32 s4, s4, s46
	s_lshl_b64 s[20:21], s[20:21], 1
	v_and_b32_e32 v16, -8, v16
	s_add_u32 s20, s43, s20
	v_ashrrev_i32_e32 v169, 31, v168
	v_add_u32_e32 v166, s4, v16
	s_addc_u32 s21, s44, s21
	v_lshlrev_b64 v[16:17], 13, v[168:169]
	v_lshl_add_u64 v[16:17], s[20:21], 0, v[16:17]
	v_ashrrev_i32_e32 v167, 31, v166
	v_lshl_add_u64 v[16:17], v[166:167], 1, v[16:17]
	v_lshlrev_b64 v[18:19], 11, v[168:169]
	v_lshl_add_u64 v[18:19], s[8:9], 0, v[18:19]
	v_lshl_add_u64 v[172:173], v[166:167], 1, v[18:19]
	v_mov_b64_e32 v[170:171], v[16:17]
	v_mov_b64_e32 v[230:231], v[250:251]
	v_mov_b32_e32 v243, v249
	v_mov_b32_e32 v251, v248
	v_mov_b32_e32 v249, 0x358637bd
	v_mov_b32_e32 v248, 0x260
	s_mov_b32 s59, 0
	s_waitcnt lgkmcnt(0)
	s_cmp_eq_u32 s5, 0
	s_cbranch_scc1 .Lmepi_z0
	s_cmp_eq_u32 s5, 3
	s_cbranch_scc1 .Lmepi_z3
	global_load_dwordx4 v[180:183], v[170:171], off nt
	global_load_dwordx4 v[184:187], v[170:171], off offset:256 nt
	global_load_dwordx4 v[188:191], v[172:173], off nt
	global_load_dwordx4 v[192:195], v[172:173], off offset:256 nt
	s_mov_b32 s58, 0x20000
	v_lshl_add_u64 v[244:245], v[170:171], 0, s[58:59]
	global_load_dwordx4 v[196:199], v[244:245], off nt
	global_load_dwordx4 v[200:203], v[244:245], off offset:256 nt
	s_mov_b32 s58, 0x8000
	v_lshl_add_u64 v[246:247], v[172:173], 0, s[58:59]
	global_load_dwordx4 v[204:207], v[246:247], off nt
	global_load_dwordx4 v[208:211], v[246:247], off offset:256 nt
	s_mov_b32 s58, 0x40000
	v_lshl_add_u64 v[252:253], v[170:171], 0, s[58:59]
	global_load_dwordx4 v[222:225], v[252:253], off nt
	global_load_dwordx4 v[226:229], v[252:253], off offset:256 nt
	s_mov_b32 s58, 0x10000
	v_lshl_add_u64 v[178:179], v[172:173], 0, s[58:59]
	global_load_dwordx4 v[234:237], v[178:179], off nt
	global_load_dwordx4 v[238:241], v[178:179], off offset:256 nt
	s_mov_b32 s58, 0x60000
	v_lshl_add_u64 v[244:245], v[170:171], 0, s[58:59]
	global_load_dwordx4 v[16:19], v[244:245], off nt
	global_load_dwordx4 v[24:27], v[244:245], off offset:256 nt
	s_mov_b32 s58, 0x18000
	v_lshl_add_u64 v[246:247], v[172:173], 0, s[58:59]
	global_load_dwordx4 v[32:35], v[246:247], off nt
	global_load_dwordx4 v[44:47], v[246:247], off offset:256 nt
	s_mov_b32 s58, 0x100000
	v_lshl_add_u64 v[252:253], v[170:171], 0, s[58:59]
	global_load_dwordx4 v[136:139], v[252:253], off nt
	global_load_dwordx4 v[148:151], v[252:253], off offset:256 nt
	s_mov_b32 s58, 0x40000
	v_lshl_add_u64 v[178:179], v[172:173], 0, s[58:59]
	global_load_dwordx4 v[152:155], v[178:179], off nt
	global_load_dwordx4 v[156:159], v[178:179], off offset:256 nt
	s_waitcnt vmcnt(17)
	v_lshlrev_b32_e32 v244, 16, v180
	v_and_b32_e32 v245, 0xffff0000, v180
	v_pk_mul_f32 v[144:145], v[144:145], v[244:245]
	v_lshlrev_b32_e32 v246, 16, v181
	v_and_b32_e32 v247, 0xffff0000, v181
	v_pk_mul_f32 v[146:147], v[146:147], v[246:247]
	v_lshlrev_b32_e32 v252, 16, v182
	v_and_b32_e32 v253, 0xffff0000, v182
	v_pk_mul_f32 v[140:141], v[140:141], v[252:253]
	v_lshlrev_b32_e32 v178, 16, v183
	v_and_b32_e32 v179, 0xffff0000, v183
	v_pk_mul_f32 v[142:143], v[142:143], v[178:179]
	v_lshlrev_b32_e32 v244, 16, v188
	v_and_b32_e32 v245, 0xffff0000, v188
	v_pk_add_f32 v[144:145], v[144:145], v[244:245]
	v_lshlrev_b32_e32 v246, 16, v189
	v_and_b32_e32 v247, 0xffff0000, v189
	v_pk_add_f32 v[146:147], v[146:147], v[246:247]
	v_lshlrev_b32_e32 v252, 16, v190
	v_and_b32_e32 v253, 0xffff0000, v190
	v_pk_add_f32 v[140:141], v[140:141], v[252:253]
	v_lshlrev_b32_e32 v178, 16, v191
	v_and_b32_e32 v179, 0xffff0000, v191
	v_pk_add_f32 v[142:143], v[142:143], v[178:179]
	v_cvt_pk_bf16_f32 v180, v144, v145
	v_cvt_pk_bf16_f32 v181, v146, v147
	v_cvt_pk_bf16_f32 v182, v140, v141
	v_cvt_pk_bf16_f32 v183, v142, v143
	global_store_dwordx4 v[172:173], v[180:183], off
	s_waitcnt vmcnt(17)
	v_lshlrev_b32_e32 v244, 16, v184
	v_and_b32_e32 v245, 0xffff0000, v184
	v_pk_mul_f32 v[132:133], v[132:133], v[244:245]
	v_lshlrev_b32_e32 v246, 16, v185
	v_and_b32_e32 v247, 0xffff0000, v185
	v_pk_mul_f32 v[134:135], v[134:135], v[246:247]
	v_lshlrev_b32_e32 v252, 16, v186
	v_and_b32_e32 v253, 0xffff0000, v186
	v_pk_mul_f32 v[128:129], v[128:129], v[252:253]
	v_lshlrev_b32_e32 v178, 16, v187
	v_and_b32_e32 v179, 0xffff0000, v187
	v_pk_mul_f32 v[130:131], v[130:131], v[178:179]
	v_lshlrev_b32_e32 v244, 16, v192
	v_and_b32_e32 v245, 0xffff0000, v192
	v_pk_add_f32 v[132:133], v[132:133], v[244:245]
	v_lshlrev_b32_e32 v246, 16, v193
	v_and_b32_e32 v247, 0xffff0000, v193
	v_pk_add_f32 v[134:135], v[134:135], v[246:247]
	v_lshlrev_b32_e32 v252, 16, v194
	v_and_b32_e32 v253, 0xffff0000, v194
	v_pk_add_f32 v[128:129], v[128:129], v[252:253]
	v_lshlrev_b32_e32 v178, 16, v195
	v_and_b32_e32 v179, 0xffff0000, v195
	v_pk_add_f32 v[130:131], v[130:131], v[178:179]
	v_cvt_pk_bf16_f32 v184, v132, v133
	v_cvt_pk_bf16_f32 v185, v134, v135
	v_cvt_pk_bf16_f32 v186, v128, v129
	v_cvt_pk_bf16_f32 v187, v130, v131
	global_store_dwordx4 v[172:173], v[184:187], off offset:256
	s_mov_b32 s58, 0x120000
	v_lshl_add_u64 v[244:245], v[170:171], 0, s[58:59]
	global_load_dwordx4 v[140:143], v[244:245], off nt
	global_load_dwordx4 v[144:147], v[244:245], off offset:256 nt
	s_mov_b32 s58, 0x48000
	v_lshl_add_u64 v[246:247], v[172:173], 0, s[58:59]
	global_load_dwordx4 v[180:183], v[246:247], off nt
	global_load_dwordx4 v[188:191], v[246:247], off offset:256 nt
	s_mov_b32 s58, 0x140000
	v_lshl_add_u64 v[252:253], v[170:171], 0, s[58:59]
	global_load_dwordx4 v[128:131], v[252:253], off nt
	global_load_dwordx4 v[132:135], v[252:253], off offset:256 nt
	s_mov_b32 s58, 0x50000
	v_lshl_add_u64 v[178:179], v[172:173], 0, s[58:59]
	global_load_dwordx4 v[184:187], v[178:179], off nt
	global_load_dwordx4 v[192:195], v[178:179], off offset:256 nt
	s_waitcnt vmcnt(23)
	v_lshlrev_b32_e32 v244, 16, v196
	v_and_b32_e32 v245, 0xffff0000, v196
	v_pk_mul_f32 v[124:125], v[124:125], v[244:245]
	v_lshlrev_b32_e32 v246, 16, v197
	v_and_b32_e32 v247, 0xffff0000, v197
	v_pk_mul_f32 v[126:127], v[126:127], v[246:247]
	v_lshlrev_b32_e32 v252, 16, v198
	v_and_b32_e32 v253, 0xffff0000, v198
	v_pk_mul_f32 v[120:121], v[120:121], v[252:253]
	v_lshlrev_b32_e32 v178, 16, v199
	v_and_b32_e32 v179, 0xffff0000, v199
	v_pk_mul_f32 v[122:123], v[122:123], v[178:179]
	v_lshlrev_b32_e32 v244, 16, v204
	v_and_b32_e32 v245, 0xffff0000, v204
	v_pk_add_f32 v[124:125], v[124:125], v[244:245]
	v_lshlrev_b32_e32 v246, 16, v205
	v_and_b32_e32 v247, 0xffff0000, v205
	v_pk_add_f32 v[126:127], v[126:127], v[246:247]
	v_lshlrev_b32_e32 v252, 16, v206
	v_and_b32_e32 v253, 0xffff0000, v206
	v_pk_add_f32 v[120:121], v[120:121], v[252:253]
	v_lshlrev_b32_e32 v178, 16, v207
	v_and_b32_e32 v179, 0xffff0000, v207
	v_pk_add_f32 v[122:123], v[122:123], v[178:179]
	v_cvt_pk_bf16_f32 v196, v124, v125
	v_cvt_pk_bf16_f32 v197, v126, v127
	v_cvt_pk_bf16_f32 v198, v120, v121
	v_cvt_pk_bf16_f32 v199, v122, v123
	s_mov_b32 s58, 0x8000
	v_lshl_add_u64 v[244:245], v[172:173], 0, s[58:59]
	global_store_dwordx4 v[244:245], v[196:199], off
	s_waitcnt vmcnt(23)
	v_lshlrev_b32_e32 v246, 16, v200
	v_and_b32_e32 v247, 0xffff0000, v200
	v_pk_mul_f32 v[116:117], v[116:117], v[246:247]
	v_lshlrev_b32_e32 v252, 16, v201
	v_and_b32_e32 v253, 0xffff0000, v201
	v_pk_mul_f32 v[118:119], v[118:119], v[252:253]
	v_lshlrev_b32_e32 v178, 16, v202
	v_and_b32_e32 v179, 0xffff0000, v202
	v_pk_mul_f32 v[112:113], v[112:113], v[178:179]
	v_lshlrev_b32_e32 v244, 16, v203
	v_and_b32_e32 v245, 0xffff0000, v203
	v_pk_mul_f32 v[114:115], v[114:115], v[244:245]
	v_lshlrev_b32_e32 v246, 16, v208
	v_and_b32_e32 v247, 0xffff0000, v208
	v_pk_add_f32 v[116:117], v[116:117], v[246:247]
	v_lshlrev_b32_e32 v252, 16, v209
	v_and_b32_e32 v253, 0xffff0000, v209
	v_pk_add_f32 v[118:119], v[118:119], v[252:253]
	v_lshlrev_b32_e32 v178, 16, v210
	v_and_b32_e32 v179, 0xffff0000, v210
	v_pk_add_f32 v[112:113], v[112:113], v[178:179]
	v_lshlrev_b32_e32 v244, 16, v211
	v_and_b32_e32 v245, 0xffff0000, v211
	v_pk_add_f32 v[114:115], v[114:115], v[244:245]
	v_cvt_pk_bf16_f32 v200, v116, v117
	v_cvt_pk_bf16_f32 v201, v118, v119
	v_cvt_pk_bf16_f32 v202, v112, v113
	v_cvt_pk_bf16_f32 v203, v114, v115
	s_mov_b32 s58, 0x8000
	v_lshl_add_u64 v[246:247], v[172:173], 0, s[58:59]
	global_store_dwordx4 v[246:247], v[200:203], off offset:256
	s_mov_b32 s58, 0x160000
	v_lshl_add_u64 v[252:253], v[170:171], 0, s[58:59]
	global_load_dwordx4 v[120:123], v[252:253], off nt
	global_load_dwordx4 v[124:127], v[252:253], off offset:256 nt
	s_mov_b32 s58, 0x58000
	v_lshl_add_u64 v[178:179], v[172:173], 0, s[58:59]
	global_load_dwordx4 v[196:199], v[178:179], off nt
	global_load_dwordx4 v[204:207], v[178:179], off offset:256 nt
	s_waitcnt vmcnt(25)
	v_lshlrev_b32_e32 v244, 16, v222
	v_and_b32_e32 v245, 0xffff0000, v222
	v_pk_mul_f32 v[108:109], v[108:109], v[244:245]
	v_lshlrev_b32_e32 v246, 16, v223
	v_and_b32_e32 v247, 0xffff0000, v223
	v_pk_mul_f32 v[110:111], v[110:111], v[246:247]
	v_lshlrev_b32_e32 v252, 16, v224
	v_and_b32_e32 v253, 0xffff0000, v224
	v_pk_mul_f32 v[104:105], v[104:105], v[252:253]
	v_lshlrev_b32_e32 v178, 16, v225
	v_and_b32_e32 v179, 0xffff0000, v225
	v_pk_mul_f32 v[106:107], v[106:107], v[178:179]
	v_lshlrev_b32_e32 v244, 16, v234
	v_and_b32_e32 v245, 0xffff0000, v234
	v_pk_add_f32 v[108:109], v[108:109], v[244:245]
	v_lshlrev_b32_e32 v246, 16, v235
	v_and_b32_e32 v247, 0xffff0000, v235
	v_pk_add_f32 v[110:111], v[110:111], v[246:247]
	v_lshlrev_b32_e32 v252, 16, v236
	v_and_b32_e32 v253, 0xffff0000, v236
	v_pk_add_f32 v[104:105], v[104:105], v[252:253]
	v_lshlrev_b32_e32 v178, 16, v237
	v_and_b32_e32 v179, 0xffff0000, v237
	v_pk_add_f32 v[106:107], v[106:107], v[178:179]
	v_cvt_pk_bf16_f32 v222, v108, v109
	v_cvt_pk_bf16_f32 v223, v110, v111
	v_cvt_pk_bf16_f32 v224, v104, v105
	v_cvt_pk_bf16_f32 v225, v106, v107
	s_mov_b32 s58, 0x10000
	v_lshl_add_u64 v[244:245], v[172:173], 0, s[58:59]
	global_store_dwordx4 v[244:245], v[222:225], off
	s_waitcnt vmcnt(25)
	v_lshlrev_b32_e32 v246, 16, v226
	v_and_b32_e32 v247, 0xffff0000, v226
	v_pk_mul_f32 v[100:101], v[100:101], v[246:247]
	v_lshlrev_b32_e32 v252, 16, v227
	v_and_b32_e32 v253, 0xffff0000, v227
	v_pk_mul_f32 v[102:103], v[102:103], v[252:253]
	v_lshlrev_b32_e32 v178, 16, v228
	v_and_b32_e32 v179, 0xffff0000, v228
	v_pk_mul_f32 v[96:97], v[96:97], v[178:179]
	v_lshlrev_b32_e32 v244, 16, v229
	v_and_b32_e32 v245, 0xffff0000, v229
	v_pk_mul_f32 v[98:99], v[98:99], v[244:245]
	v_lshlrev_b32_e32 v246, 16, v238
	v_and_b32_e32 v247, 0xffff0000, v238
	v_pk_add_f32 v[100:101], v[100:101], v[246:247]
	v_lshlrev_b32_e32 v252, 16, v239
	v_and_b32_e32 v253, 0xffff0000, v239
	v_pk_add_f32 v[102:103], v[102:103], v[252:253]
	v_lshlrev_b32_e32 v178, 16, v240
	v_and_b32_e32 v179, 0xffff0000, v240
	v_pk_add_f32 v[96:97], v[96:97], v[178:179]
	v_lshlrev_b32_e32 v244, 16, v241
	v_and_b32_e32 v245, 0xffff0000, v241
	v_pk_add_f32 v[98:99], v[98:99], v[244:245]
	v_cvt_pk_bf16_f32 v226, v100, v101
	v_cvt_pk_bf16_f32 v227, v102, v103
	v_cvt_pk_bf16_f32 v228, v96, v97
	v_cvt_pk_bf16_f32 v229, v98, v99
	s_mov_b32 s58, 0x10000
	v_lshl_add_u64 v[246:247], v[172:173], 0, s[58:59]
	global_store_dwordx4 v[246:247], v[226:229], off offset:256
	s_waitcnt vmcnt(23)
	v_lshlrev_b32_e32 v252, 16, v16
	v_and_b32_e32 v253, 0xffff0000, v16
	v_pk_mul_f32 v[92:93], v[92:93], v[252:253]
	v_lshlrev_b32_e32 v178, 16, v17
	v_and_b32_e32 v179, 0xffff0000, v17
	v_pk_mul_f32 v[94:95], v[94:95], v[178:179]
	v_lshlrev_b32_e32 v244, 16, v18
	v_and_b32_e32 v245, 0xffff0000, v18
	v_pk_mul_f32 v[88:89], v[88:89], v[244:245]
	v_lshlrev_b32_e32 v246, 16, v19
	v_and_b32_e32 v247, 0xffff0000, v19
	v_pk_mul_f32 v[90:91], v[90:91], v[246:247]
	v_lshlrev_b32_e32 v252, 16, v32
	v_and_b32_e32 v253, 0xffff0000, v32
	v_pk_add_f32 v[92:93], v[92:93], v[252:253]
	v_lshlrev_b32_e32 v178, 16, v33
	v_and_b32_e32 v179, 0xffff0000, v33
	v_pk_add_f32 v[94:95], v[94:95], v[178:179]
	v_lshlrev_b32_e32 v244, 16, v34
	v_and_b32_e32 v245, 0xffff0000, v34
	v_pk_add_f32 v[88:89], v[88:89], v[244:245]
	v_lshlrev_b32_e32 v246, 16, v35
	v_and_b32_e32 v247, 0xffff0000, v35
	v_pk_add_f32 v[90:91], v[90:91], v[246:247]
	v_cvt_pk_bf16_f32 v16, v92, v93
	v_cvt_pk_bf16_f32 v17, v94, v95
	v_cvt_pk_bf16_f32 v18, v88, v89
	v_cvt_pk_bf16_f32 v19, v90, v91
	s_mov_b32 s58, 0x18000
	v_lshl_add_u64 v[252:253], v[172:173], 0, s[58:59]
	global_store_dwordx4 v[252:253], v[16:19], off
	s_waitcnt vmcnt(23)
	v_lshlrev_b32_e32 v178, 16, v24
	v_and_b32_e32 v179, 0xffff0000, v24
	v_pk_mul_f32 v[84:85], v[84:85], v[178:179]
	v_lshlrev_b32_e32 v244, 16, v25
	v_and_b32_e32 v245, 0xffff0000, v25
	v_pk_mul_f32 v[86:87], v[86:87], v[244:245]
	v_lshlrev_b32_e32 v246, 16, v26
	v_and_b32_e32 v247, 0xffff0000, v26
	v_pk_mul_f32 v[80:81], v[80:81], v[246:247]
	v_lshlrev_b32_e32 v252, 16, v27
	v_and_b32_e32 v253, 0xffff0000, v27
	v_pk_mul_f32 v[82:83], v[82:83], v[252:253]
	v_lshlrev_b32_e32 v178, 16, v44
	v_and_b32_e32 v179, 0xffff0000, v44
	v_pk_add_f32 v[84:85], v[84:85], v[178:179]
	v_lshlrev_b32_e32 v244, 16, v45
	v_and_b32_e32 v245, 0xffff0000, v45
	v_pk_add_f32 v[86:87], v[86:87], v[244:245]
	v_lshlrev_b32_e32 v246, 16, v46
	v_and_b32_e32 v247, 0xffff0000, v46
	v_pk_add_f32 v[80:81], v[80:81], v[246:247]
	v_lshlrev_b32_e32 v252, 16, v47
	v_and_b32_e32 v253, 0xffff0000, v47
	v_pk_add_f32 v[82:83], v[82:83], v[252:253]
	v_cvt_pk_bf16_f32 v24, v84, v85
	v_cvt_pk_bf16_f32 v25, v86, v87
	v_cvt_pk_bf16_f32 v26, v80, v81
	v_cvt_pk_bf16_f32 v27, v82, v83
	s_mov_b32 s58, 0x18000
	v_lshl_add_u64 v[178:179], v[172:173], 0, s[58:59]
	global_store_dwordx4 v[178:179], v[24:27], off offset:256
	s_waitcnt vmcnt(21)
	v_lshlrev_b32_e32 v244, 16, v136
	v_and_b32_e32 v245, 0xffff0000, v136
	v_pk_mul_f32 v[76:77], v[76:77], v[244:245]
	v_lshlrev_b32_e32 v246, 16, v137
	v_and_b32_e32 v247, 0xffff0000, v137
	v_pk_mul_f32 v[78:79], v[78:79], v[246:247]
	v_lshlrev_b32_e32 v252, 16, v138
	v_and_b32_e32 v253, 0xffff0000, v138
	v_pk_mul_f32 v[72:73], v[72:73], v[252:253]
	v_lshlrev_b32_e32 v178, 16, v139
	v_and_b32_e32 v179, 0xffff0000, v139
	v_pk_mul_f32 v[74:75], v[74:75], v[178:179]
	v_lshlrev_b32_e32 v244, 16, v152
	v_and_b32_e32 v245, 0xffff0000, v152
	v_pk_add_f32 v[76:77], v[76:77], v[244:245]
	v_lshlrev_b32_e32 v246, 16, v153
	v_and_b32_e32 v247, 0xffff0000, v153
	v_pk_add_f32 v[78:79], v[78:79], v[246:247]
	v_lshlrev_b32_e32 v252, 16, v154
	v_and_b32_e32 v253, 0xffff0000, v154
	v_pk_add_f32 v[72:73], v[72:73], v[252:253]
	v_lshlrev_b32_e32 v178, 16, v155
	v_and_b32_e32 v179, 0xffff0000, v155
	v_pk_add_f32 v[74:75], v[74:75], v[178:179]
	v_cvt_pk_bf16_f32 v136, v76, v77
	v_cvt_pk_bf16_f32 v137, v78, v79
	v_cvt_pk_bf16_f32 v138, v72, v73
	v_cvt_pk_bf16_f32 v139, v74, v75
	s_mov_b32 s58, 0x40000
	v_lshl_add_u64 v[244:245], v[172:173], 0, s[58:59]
	global_store_dwordx4 v[244:245], v[136:139], off
	s_waitcnt vmcnt(21)
	v_lshlrev_b32_e32 v246, 16, v148
	v_and_b32_e32 v247, 0xffff0000, v148
	v_pk_mul_f32 v[68:69], v[68:69], v[246:247]
	v_lshlrev_b32_e32 v252, 16, v149
	v_and_b32_e32 v253, 0xffff0000, v149
	v_pk_mul_f32 v[70:71], v[70:71], v[252:253]
	v_lshlrev_b32_e32 v178, 16, v150
	v_and_b32_e32 v179, 0xffff0000, v150
	v_pk_mul_f32 v[64:65], v[64:65], v[178:179]
	v_lshlrev_b32_e32 v244, 16, v151
	v_and_b32_e32 v245, 0xffff0000, v151
	v_pk_mul_f32 v[66:67], v[66:67], v[244:245]
	v_lshlrev_b32_e32 v246, 16, v156
	v_and_b32_e32 v247, 0xffff0000, v156
	v_pk_add_f32 v[68:69], v[68:69], v[246:247]
	v_lshlrev_b32_e32 v252, 16, v157
	v_and_b32_e32 v253, 0xffff0000, v157
	v_pk_add_f32 v[70:71], v[70:71], v[252:253]
	v_lshlrev_b32_e32 v178, 16, v158
	v_and_b32_e32 v179, 0xffff0000, v158
	v_pk_add_f32 v[64:65], v[64:65], v[178:179]
	v_lshlrev_b32_e32 v244, 16, v159
	v_and_b32_e32 v245, 0xffff0000, v159
	v_pk_add_f32 v[66:67], v[66:67], v[244:245]
	v_cvt_pk_bf16_f32 v148, v68, v69
	v_cvt_pk_bf16_f32 v149, v70, v71
	v_cvt_pk_bf16_f32 v150, v64, v65
	v_cvt_pk_bf16_f32 v151, v66, v67
	s_mov_b32 s58, 0x40000
	v_lshl_add_u64 v[246:247], v[172:173], 0, s[58:59]
	global_store_dwordx4 v[246:247], v[148:151], off offset:256
	s_waitcnt vmcnt(17)
	v_lshlrev_b32_e32 v252, 16, v140
	v_and_b32_e32 v253, 0xffff0000, v140
	v_pk_mul_f32 v[60:61], v[60:61], v[252:253]
	v_lshlrev_b32_e32 v178, 16, v141
	v_and_b32_e32 v179, 0xffff0000, v141
	v_pk_mul_f32 v[62:63], v[62:63], v[178:179]
	v_lshlrev_b32_e32 v244, 16, v142
	v_and_b32_e32 v245, 0xffff0000, v142
	v_pk_mul_f32 v[56:57], v[56:57], v[244:245]
	v_lshlrev_b32_e32 v246, 16, v143
	v_and_b32_e32 v247, 0xffff0000, v143
	v_pk_mul_f32 v[58:59], v[58:59], v[246:247]
	v_lshlrev_b32_e32 v252, 16, v180
	v_and_b32_e32 v253, 0xffff0000, v180
	v_pk_add_f32 v[60:61], v[60:61], v[252:253]
	v_lshlrev_b32_e32 v178, 16, v181
	v_and_b32_e32 v179, 0xffff0000, v181
	v_pk_add_f32 v[62:63], v[62:63], v[178:179]
	v_lshlrev_b32_e32 v244, 16, v182
	v_and_b32_e32 v245, 0xffff0000, v182
	v_pk_add_f32 v[56:57], v[56:57], v[244:245]
	v_lshlrev_b32_e32 v246, 16, v183
	v_and_b32_e32 v247, 0xffff0000, v183
	v_pk_add_f32 v[58:59], v[58:59], v[246:247]
	v_cvt_pk_bf16_f32 v140, v60, v61
	v_cvt_pk_bf16_f32 v141, v62, v63
	v_cvt_pk_bf16_f32 v142, v56, v57
	v_cvt_pk_bf16_f32 v143, v58, v59
	s_mov_b32 s58, 0x48000
	v_lshl_add_u64 v[252:253], v[172:173], 0, s[58:59]
	global_store_dwordx4 v[252:253], v[140:143], off
	s_waitcnt vmcnt(17)
	v_lshlrev_b32_e32 v178, 16, v144
	v_and_b32_e32 v179, 0xffff0000, v144
	v_pk_mul_f32 v[52:53], v[52:53], v[178:179]
	v_lshlrev_b32_e32 v244, 16, v145
	v_and_b32_e32 v245, 0xffff0000, v145
	v_pk_mul_f32 v[54:55], v[54:55], v[244:245]
	v_lshlrev_b32_e32 v246, 16, v146
	v_and_b32_e32 v247, 0xffff0000, v146
	v_pk_mul_f32 v[48:49], v[48:49], v[246:247]
	v_lshlrev_b32_e32 v252, 16, v147
	v_and_b32_e32 v253, 0xffff0000, v147
	v_pk_mul_f32 v[50:51], v[50:51], v[252:253]
	v_lshlrev_b32_e32 v178, 16, v188
	v_and_b32_e32 v179, 0xffff0000, v188
	v_pk_add_f32 v[52:53], v[52:53], v[178:179]
	v_lshlrev_b32_e32 v244, 16, v189
	v_and_b32_e32 v245, 0xffff0000, v189
	v_pk_add_f32 v[54:55], v[54:55], v[244:245]
	v_lshlrev_b32_e32 v246, 16, v190
	v_and_b32_e32 v247, 0xffff0000, v190
	v_pk_add_f32 v[48:49], v[48:49], v[246:247]
	v_lshlrev_b32_e32 v252, 16, v191
	v_and_b32_e32 v253, 0xffff0000, v191
	v_pk_add_f32 v[50:51], v[50:51], v[252:253]
	v_cvt_pk_bf16_f32 v144, v52, v53
	v_cvt_pk_bf16_f32 v145, v54, v55
	v_cvt_pk_bf16_f32 v146, v48, v49
	v_cvt_pk_bf16_f32 v147, v50, v51
	s_mov_b32 s58, 0x48000
	v_lshl_add_u64 v[178:179], v[172:173], 0, s[58:59]
	global_store_dwordx4 v[178:179], v[144:147], off offset:256
	s_waitcnt vmcnt(15)
	v_lshlrev_b32_e32 v244, 16, v128
	v_and_b32_e32 v245, 0xffff0000, v128
	v_pk_mul_f32 v[40:41], v[40:41], v[244:245]
	v_lshlrev_b32_e32 v246, 16, v129
	v_and_b32_e32 v247, 0xffff0000, v129
	v_pk_mul_f32 v[42:43], v[42:43], v[246:247]
	v_lshlrev_b32_e32 v252, 16, v130
	v_and_b32_e32 v253, 0xffff0000, v130
	v_pk_mul_f32 v[36:37], v[36:37], v[252:253]
	v_lshlrev_b32_e32 v178, 16, v131
	v_and_b32_e32 v179, 0xffff0000, v131
	v_pk_mul_f32 v[38:39], v[38:39], v[178:179]
	v_lshlrev_b32_e32 v244, 16, v184
	v_and_b32_e32 v245, 0xffff0000, v184
	v_pk_add_f32 v[40:41], v[40:41], v[244:245]
	v_lshlrev_b32_e32 v246, 16, v185
	v_and_b32_e32 v247, 0xffff0000, v185
	v_pk_add_f32 v[42:43], v[42:43], v[246:247]
	v_lshlrev_b32_e32 v252, 16, v186
	v_and_b32_e32 v253, 0xffff0000, v186
	v_pk_add_f32 v[36:37], v[36:37], v[252:253]
	v_lshlrev_b32_e32 v178, 16, v187
	v_and_b32_e32 v179, 0xffff0000, v187
	v_pk_add_f32 v[38:39], v[38:39], v[178:179]
	v_cvt_pk_bf16_f32 v128, v40, v41
	v_cvt_pk_bf16_f32 v129, v42, v43
	v_cvt_pk_bf16_f32 v130, v36, v37
	v_cvt_pk_bf16_f32 v131, v38, v39
	s_mov_b32 s58, 0x50000
	v_lshl_add_u64 v[244:245], v[172:173], 0, s[58:59]
	global_store_dwordx4 v[244:245], v[128:131], off
	s_waitcnt vmcnt(15)
	v_lshlrev_b32_e32 v246, 16, v132
	v_and_b32_e32 v247, 0xffff0000, v132
	v_pk_mul_f32 v[28:29], v[28:29], v[246:247]
	v_lshlrev_b32_e32 v252, 16, v133
	v_and_b32_e32 v253, 0xffff0000, v133
	v_pk_mul_f32 v[30:31], v[30:31], v[252:253]
	v_lshlrev_b32_e32 v178, 16, v134
	v_and_b32_e32 v179, 0xffff0000, v134
	v_pk_mul_f32 v[20:21], v[20:21], v[178:179]
	v_lshlrev_b32_e32 v244, 16, v135
	v_and_b32_e32 v245, 0xffff0000, v135
	v_pk_mul_f32 v[22:23], v[22:23], v[244:245]
	v_lshlrev_b32_e32 v246, 16, v192
	v_and_b32_e32 v247, 0xffff0000, v192
	v_pk_add_f32 v[28:29], v[28:29], v[246:247]
	v_lshlrev_b32_e32 v252, 16, v193
	v_and_b32_e32 v253, 0xffff0000, v193
	v_pk_add_f32 v[30:31], v[30:31], v[252:253]
	v_lshlrev_b32_e32 v178, 16, v194
	v_and_b32_e32 v179, 0xffff0000, v194
	v_pk_add_f32 v[20:21], v[20:21], v[178:179]
	v_lshlrev_b32_e32 v244, 16, v195
	v_and_b32_e32 v245, 0xffff0000, v195
	v_pk_add_f32 v[22:23], v[22:23], v[244:245]
	v_cvt_pk_bf16_f32 v132, v28, v29
	v_cvt_pk_bf16_f32 v133, v30, v31
	v_cvt_pk_bf16_f32 v134, v20, v21
	v_cvt_pk_bf16_f32 v135, v22, v23
	s_mov_b32 s58, 0x50000
	v_lshl_add_u64 v[246:247], v[172:173], 0, s[58:59]
	global_store_dwordx4 v[246:247], v[132:135], off offset:256
	s_waitcnt vmcnt(11)
	v_lshlrev_b32_e32 v252, 16, v120
	v_and_b32_e32 v253, 0xffff0000, v120
	v_pk_mul_f32 v[12:13], v[12:13], v[252:253]
	v_lshlrev_b32_e32 v178, 16, v121
	v_and_b32_e32 v179, 0xffff0000, v121
	v_pk_mul_f32 v[14:15], v[14:15], v[178:179]
	v_lshlrev_b32_e32 v244, 16, v122
	v_and_b32_e32 v245, 0xffff0000, v122
	v_pk_mul_f32 v[8:9], v[8:9], v[244:245]
	v_lshlrev_b32_e32 v246, 16, v123
	v_and_b32_e32 v247, 0xffff0000, v123
	v_pk_mul_f32 v[10:11], v[10:11], v[246:247]
	v_lshlrev_b32_e32 v252, 16, v196
	v_and_b32_e32 v253, 0xffff0000, v196
	v_pk_add_f32 v[12:13], v[12:13], v[252:253]
	v_lshlrev_b32_e32 v178, 16, v197
	v_and_b32_e32 v179, 0xffff0000, v197
	v_pk_add_f32 v[14:15], v[14:15], v[178:179]
	v_lshlrev_b32_e32 v244, 16, v198
	v_and_b32_e32 v245, 0xffff0000, v198
	v_pk_add_f32 v[8:9], v[8:9], v[244:245]
	v_lshlrev_b32_e32 v246, 16, v199
	v_and_b32_e32 v247, 0xffff0000, v199
	v_pk_add_f32 v[10:11], v[10:11], v[246:247]
	v_cvt_pk_bf16_f32 v120, v12, v13
	v_cvt_pk_bf16_f32 v121, v14, v15
	v_cvt_pk_bf16_f32 v122, v8, v9
	v_cvt_pk_bf16_f32 v123, v10, v11
	s_mov_b32 s58, 0x58000
	v_lshl_add_u64 v[252:253], v[172:173], 0, s[58:59]
	global_store_dwordx4 v[252:253], v[120:123], off
	s_waitcnt vmcnt(11)
	v_lshlrev_b32_e32 v178, 16, v124
	v_and_b32_e32 v179, 0xffff0000, v124
	v_pk_mul_f32 v[4:5], v[4:5], v[178:179]
	v_lshlrev_b32_e32 v244, 16, v125
	v_and_b32_e32 v245, 0xffff0000, v125
	v_pk_mul_f32 v[6:7], v[6:7], v[244:245]
	v_lshlrev_b32_e32 v246, 16, v126
	v_and_b32_e32 v247, 0xffff0000, v126
	v_pk_mul_f32 v[0:1], v[0:1], v[246:247]
	v_lshlrev_b32_e32 v252, 16, v127
	v_and_b32_e32 v253, 0xffff0000, v127
	v_pk_mul_f32 v[2:3], v[2:3], v[252:253]
	v_lshlrev_b32_e32 v178, 16, v204
	v_and_b32_e32 v179, 0xffff0000, v204
	v_pk_add_f32 v[4:5], v[4:5], v[178:179]
	v_lshlrev_b32_e32 v244, 16, v205
	v_and_b32_e32 v245, 0xffff0000, v205
	v_pk_add_f32 v[6:7], v[6:7], v[244:245]
	v_lshlrev_b32_e32 v246, 16, v206
	v_and_b32_e32 v247, 0xffff0000, v206
	v_pk_add_f32 v[0:1], v[0:1], v[246:247]
	v_lshlrev_b32_e32 v252, 16, v207
	v_and_b32_e32 v253, 0xffff0000, v207
	v_pk_add_f32 v[2:3], v[2:3], v[252:253]
	v_cvt_pk_bf16_f32 v124, v4, v5
	v_cvt_pk_bf16_f32 v125, v6, v7
	v_cvt_pk_bf16_f32 v126, v0, v1
	v_cvt_pk_bf16_f32 v127, v2, v3
	s_mov_b32 s58, 0x58000
	v_lshl_add_u64 v[178:179], v[172:173], 0, s[58:59]
	global_store_dwordx4 v[178:179], v[124:127], off offset:256
	s_branch .Lmepi_done
.Lmepi_z3:
	global_load_dwordx4 v[180:183], v[170:171], off nt
	global_load_dwordx4 v[184:187], v[170:171], off offset:256 nt
	global_load_dwordx4 v[188:191], v[172:173], off nt
	global_load_dwordx4 v[192:195], v[172:173], off offset:256 nt
	s_mov_b32 s58, 0x20000
	v_lshl_add_u64 v[244:245], v[170:171], 0, s[58:59]
	global_load_dwordx4 v[196:199], v[244:245], off nt
	global_load_dwordx4 v[200:203], v[244:245], off offset:256 nt
	s_mov_b32 s58, 0x8000
	v_lshl_add_u64 v[246:247], v[172:173], 0, s[58:59]
	global_load_dwordx4 v[204:207], v[246:247], off nt
	global_load_dwordx4 v[208:211], v[246:247], off offset:256 nt
	s_mov_b32 s58, 0x40000
	v_lshl_add_u64 v[252:253], v[170:171], 0, s[58:59]
	global_load_dwordx4 v[222:225], v[252:253], off nt
	global_load_dwordx4 v[226:229], v[252:253], off offset:256 nt
	s_mov_b32 s58, 0x10000
	v_lshl_add_u64 v[178:179], v[172:173], 0, s[58:59]
	global_load_dwordx4 v[234:237], v[178:179], off nt
	global_load_dwordx4 v[238:241], v[178:179], off offset:256 nt
	s_mov_b32 s58, 0x60000
	v_lshl_add_u64 v[244:245], v[170:171], 0, s[58:59]
	global_load_dwordx4 v[16:19], v[244:245], off nt
	global_load_dwordx4 v[24:27], v[244:245], off offset:256 nt
	s_mov_b32 s58, 0x18000
	v_lshl_add_u64 v[246:247], v[172:173], 0, s[58:59]
	global_load_dwordx4 v[32:35], v[246:247], off nt
	global_load_dwordx4 v[44:47], v[246:247], off offset:256 nt
	s_mov_b32 s58, 0x100000
	v_lshl_add_u64 v[252:253], v[170:171], 0, s[58:59]
	global_load_dwordx4 v[136:139], v[252:253], off nt
	global_load_dwordx4 v[148:151], v[252:253], off offset:256 nt
	s_mov_b32 s58, 0x40000
	v_lshl_add_u64 v[178:179], v[172:173], 0, s[58:59]
	global_load_dwordx4 v[152:155], v[178:179], off nt
	global_load_dwordx4 v[156:159], v[178:179], off offset:256 nt
	s_waitcnt vmcnt(17)
	v_lshlrev_b32_e32 v244, 16, v180
	v_and_b32_e32 v245, 0xffff0000, v180
	v_pk_mul_f32 v[144:145], v[144:145], v[244:245]
	v_lshlrev_b32_e32 v246, 16, v181
	v_and_b32_e32 v247, 0xffff0000, v181
	v_pk_mul_f32 v[146:147], v[146:147], v[246:247]
	v_lshlrev_b32_e32 v252, 16, v182
	v_and_b32_e32 v253, 0xffff0000, v182
	v_pk_mul_f32 v[140:141], v[140:141], v[252:253]
	v_lshlrev_b32_e32 v178, 16, v183
	v_and_b32_e32 v179, 0xffff0000, v183
	v_pk_mul_f32 v[142:143], v[142:143], v[178:179]
	v_lshlrev_b32_e32 v244, 16, v188
	v_and_b32_e32 v245, 0xffff0000, v188
	v_pk_add_f32 v[144:145], v[144:145], v[244:245]
	v_lshlrev_b32_e32 v246, 16, v189
	v_and_b32_e32 v247, 0xffff0000, v189
	v_pk_add_f32 v[146:147], v[146:147], v[246:247]
	v_lshlrev_b32_e32 v252, 16, v190
	v_and_b32_e32 v253, 0xffff0000, v190
	v_pk_add_f32 v[140:141], v[140:141], v[252:253]
	v_lshlrev_b32_e32 v178, 16, v191
	v_and_b32_e32 v179, 0xffff0000, v191
	v_pk_add_f32 v[142:143], v[142:143], v[178:179]
	v_cvt_pk_bf16_f32 v180, v144, v145
	v_cvt_pk_bf16_f32 v181, v146, v147
	v_cvt_pk_bf16_f32 v182, v140, v141
	v_cvt_pk_bf16_f32 v183, v142, v143
	global_store_dwordx4 v[172:173], v[180:183], off sc1
	s_waitcnt vmcnt(17)
	v_lshlrev_b32_e32 v244, 16, v184
	v_and_b32_e32 v245, 0xffff0000, v184
	v_pk_mul_f32 v[132:133], v[132:133], v[244:245]
	v_lshlrev_b32_e32 v246, 16, v185
	v_and_b32_e32 v247, 0xffff0000, v185
	v_pk_mul_f32 v[134:135], v[134:135], v[246:247]
	v_lshlrev_b32_e32 v252, 16, v186
	v_and_b32_e32 v253, 0xffff0000, v186
	v_pk_mul_f32 v[128:129], v[128:129], v[252:253]
	v_lshlrev_b32_e32 v178, 16, v187
	v_and_b32_e32 v179, 0xffff0000, v187
	v_pk_mul_f32 v[130:131], v[130:131], v[178:179]
	v_lshlrev_b32_e32 v244, 16, v192
	v_and_b32_e32 v245, 0xffff0000, v192
	v_pk_add_f32 v[132:133], v[132:133], v[244:245]
	v_lshlrev_b32_e32 v246, 16, v193
	v_and_b32_e32 v247, 0xffff0000, v193
	v_pk_add_f32 v[134:135], v[134:135], v[246:247]
	v_lshlrev_b32_e32 v252, 16, v194
	v_and_b32_e32 v253, 0xffff0000, v194
	v_pk_add_f32 v[128:129], v[128:129], v[252:253]
	v_lshlrev_b32_e32 v178, 16, v195
	v_and_b32_e32 v179, 0xffff0000, v195
	v_pk_add_f32 v[130:131], v[130:131], v[178:179]
	v_cvt_pk_bf16_f32 v184, v132, v133
	v_cvt_pk_bf16_f32 v185, v134, v135
	v_cvt_pk_bf16_f32 v186, v128, v129
	v_cvt_pk_bf16_f32 v187, v130, v131
	global_store_dwordx4 v[172:173], v[184:187], off offset:256 sc1
	s_mov_b32 s58, 0x120000
	v_lshl_add_u64 v[244:245], v[170:171], 0, s[58:59]
	global_load_dwordx4 v[140:143], v[244:245], off nt
	global_load_dwordx4 v[144:147], v[244:245], off offset:256 nt
	s_mov_b32 s58, 0x48000
	v_lshl_add_u64 v[246:247], v[172:173], 0, s[58:59]
	global_load_dwordx4 v[180:183], v[246:247], off nt
	global_load_dwordx4 v[188:191], v[246:247], off offset:256 nt
	s_mov_b32 s58, 0x140000
	v_lshl_add_u64 v[252:253], v[170:171], 0, s[58:59]
	global_load_dwordx4 v[128:131], v[252:253], off nt
	global_load_dwordx4 v[132:135], v[252:253], off offset:256 nt
	s_mov_b32 s58, 0x50000
	v_lshl_add_u64 v[178:179], v[172:173], 0, s[58:59]
	global_load_dwordx4 v[184:187], v[178:179], off nt
	global_load_dwordx4 v[192:195], v[178:179], off offset:256 nt
	s_waitcnt vmcnt(23)
	v_lshlrev_b32_e32 v244, 16, v196
	v_and_b32_e32 v245, 0xffff0000, v196
	v_pk_mul_f32 v[124:125], v[124:125], v[244:245]
	v_lshlrev_b32_e32 v246, 16, v197
	v_and_b32_e32 v247, 0xffff0000, v197
	v_pk_mul_f32 v[126:127], v[126:127], v[246:247]
	v_lshlrev_b32_e32 v252, 16, v198
	v_and_b32_e32 v253, 0xffff0000, v198
	v_pk_mul_f32 v[120:121], v[120:121], v[252:253]
	v_lshlrev_b32_e32 v178, 16, v199
	v_and_b32_e32 v179, 0xffff0000, v199
	v_pk_mul_f32 v[122:123], v[122:123], v[178:179]
	v_lshlrev_b32_e32 v244, 16, v204
	v_and_b32_e32 v245, 0xffff0000, v204
	v_pk_add_f32 v[124:125], v[124:125], v[244:245]
	v_lshlrev_b32_e32 v246, 16, v205
	v_and_b32_e32 v247, 0xffff0000, v205
	v_pk_add_f32 v[126:127], v[126:127], v[246:247]
	v_lshlrev_b32_e32 v252, 16, v206
	v_and_b32_e32 v253, 0xffff0000, v206
	v_pk_add_f32 v[120:121], v[120:121], v[252:253]
	v_lshlrev_b32_e32 v178, 16, v207
	v_and_b32_e32 v179, 0xffff0000, v207
	v_pk_add_f32 v[122:123], v[122:123], v[178:179]
	v_cvt_pk_bf16_f32 v196, v124, v125
	v_cvt_pk_bf16_f32 v197, v126, v127
	v_cvt_pk_bf16_f32 v198, v120, v121
	v_cvt_pk_bf16_f32 v199, v122, v123
	s_mov_b32 s58, 0x8000
	v_lshl_add_u64 v[244:245], v[172:173], 0, s[58:59]
	global_store_dwordx4 v[244:245], v[196:199], off sc1
	s_waitcnt vmcnt(23)
	v_lshlrev_b32_e32 v246, 16, v200
	v_and_b32_e32 v247, 0xffff0000, v200
	v_pk_mul_f32 v[116:117], v[116:117], v[246:247]
	v_lshlrev_b32_e32 v252, 16, v201
	v_and_b32_e32 v253, 0xffff0000, v201
	v_pk_mul_f32 v[118:119], v[118:119], v[252:253]
	v_lshlrev_b32_e32 v178, 16, v202
	v_and_b32_e32 v179, 0xffff0000, v202
	v_pk_mul_f32 v[112:113], v[112:113], v[178:179]
	v_lshlrev_b32_e32 v244, 16, v203
	v_and_b32_e32 v245, 0xffff0000, v203
	v_pk_mul_f32 v[114:115], v[114:115], v[244:245]
	v_lshlrev_b32_e32 v246, 16, v208
	v_and_b32_e32 v247, 0xffff0000, v208
	v_pk_add_f32 v[116:117], v[116:117], v[246:247]
	v_lshlrev_b32_e32 v252, 16, v209
	v_and_b32_e32 v253, 0xffff0000, v209
	v_pk_add_f32 v[118:119], v[118:119], v[252:253]
	v_lshlrev_b32_e32 v178, 16, v210
	v_and_b32_e32 v179, 0xffff0000, v210
	v_pk_add_f32 v[112:113], v[112:113], v[178:179]
	v_lshlrev_b32_e32 v244, 16, v211
	v_and_b32_e32 v245, 0xffff0000, v211
	v_pk_add_f32 v[114:115], v[114:115], v[244:245]
	v_cvt_pk_bf16_f32 v200, v116, v117
	v_cvt_pk_bf16_f32 v201, v118, v119
	v_cvt_pk_bf16_f32 v202, v112, v113
	v_cvt_pk_bf16_f32 v203, v114, v115
	s_mov_b32 s58, 0x8000
	v_lshl_add_u64 v[246:247], v[172:173], 0, s[58:59]
	global_store_dwordx4 v[246:247], v[200:203], off offset:256 sc1
	s_mov_b32 s58, 0x160000
	v_lshl_add_u64 v[252:253], v[170:171], 0, s[58:59]
	global_load_dwordx4 v[120:123], v[252:253], off nt
	global_load_dwordx4 v[124:127], v[252:253], off offset:256 nt
	s_mov_b32 s58, 0x58000
	v_lshl_add_u64 v[178:179], v[172:173], 0, s[58:59]
	global_load_dwordx4 v[196:199], v[178:179], off nt
	global_load_dwordx4 v[204:207], v[178:179], off offset:256 nt
	s_waitcnt vmcnt(25)
	v_lshlrev_b32_e32 v244, 16, v222
	v_and_b32_e32 v245, 0xffff0000, v222
	v_pk_mul_f32 v[108:109], v[108:109], v[244:245]
	v_lshlrev_b32_e32 v246, 16, v223
	v_and_b32_e32 v247, 0xffff0000, v223
	v_pk_mul_f32 v[110:111], v[110:111], v[246:247]
	v_lshlrev_b32_e32 v252, 16, v224
	v_and_b32_e32 v253, 0xffff0000, v224
	v_pk_mul_f32 v[104:105], v[104:105], v[252:253]
	v_lshlrev_b32_e32 v178, 16, v225
	v_and_b32_e32 v179, 0xffff0000, v225
	v_pk_mul_f32 v[106:107], v[106:107], v[178:179]
	v_lshlrev_b32_e32 v244, 16, v234
	v_and_b32_e32 v245, 0xffff0000, v234
	v_pk_add_f32 v[108:109], v[108:109], v[244:245]
	v_lshlrev_b32_e32 v246, 16, v235
	v_and_b32_e32 v247, 0xffff0000, v235
	v_pk_add_f32 v[110:111], v[110:111], v[246:247]
	v_lshlrev_b32_e32 v252, 16, v236
	v_and_b32_e32 v253, 0xffff0000, v236
	v_pk_add_f32 v[104:105], v[104:105], v[252:253]
	v_lshlrev_b32_e32 v178, 16, v237
	v_and_b32_e32 v179, 0xffff0000, v237
	v_pk_add_f32 v[106:107], v[106:107], v[178:179]
	v_cvt_pk_bf16_f32 v222, v108, v109
	v_cvt_pk_bf16_f32 v223, v110, v111
	v_cvt_pk_bf16_f32 v224, v104, v105
	v_cvt_pk_bf16_f32 v225, v106, v107
	s_mov_b32 s58, 0x10000
	v_lshl_add_u64 v[244:245], v[172:173], 0, s[58:59]
	global_store_dwordx4 v[244:245], v[222:225], off sc1
	s_waitcnt vmcnt(25)
	v_lshlrev_b32_e32 v246, 16, v226
	v_and_b32_e32 v247, 0xffff0000, v226
	v_pk_mul_f32 v[100:101], v[100:101], v[246:247]
	v_lshlrev_b32_e32 v252, 16, v227
	v_and_b32_e32 v253, 0xffff0000, v227
	v_pk_mul_f32 v[102:103], v[102:103], v[252:253]
	v_lshlrev_b32_e32 v178, 16, v228
	v_and_b32_e32 v179, 0xffff0000, v228
	v_pk_mul_f32 v[96:97], v[96:97], v[178:179]
	v_lshlrev_b32_e32 v244, 16, v229
	v_and_b32_e32 v245, 0xffff0000, v229
	v_pk_mul_f32 v[98:99], v[98:99], v[244:245]
	v_lshlrev_b32_e32 v246, 16, v238
	v_and_b32_e32 v247, 0xffff0000, v238
	v_pk_add_f32 v[100:101], v[100:101], v[246:247]
	v_lshlrev_b32_e32 v252, 16, v239
	v_and_b32_e32 v253, 0xffff0000, v239
	v_pk_add_f32 v[102:103], v[102:103], v[252:253]
	v_lshlrev_b32_e32 v178, 16, v240
	v_and_b32_e32 v179, 0xffff0000, v240
	v_pk_add_f32 v[96:97], v[96:97], v[178:179]
	v_lshlrev_b32_e32 v244, 16, v241
	v_and_b32_e32 v245, 0xffff0000, v241
	v_pk_add_f32 v[98:99], v[98:99], v[244:245]
	v_cvt_pk_bf16_f32 v226, v100, v101
	v_cvt_pk_bf16_f32 v227, v102, v103
	v_cvt_pk_bf16_f32 v228, v96, v97
	v_cvt_pk_bf16_f32 v229, v98, v99
	s_mov_b32 s58, 0x10000
	v_lshl_add_u64 v[246:247], v[172:173], 0, s[58:59]
	global_store_dwordx4 v[246:247], v[226:229], off offset:256 sc1
	s_waitcnt vmcnt(23)
	v_lshlrev_b32_e32 v252, 16, v16
	v_and_b32_e32 v253, 0xffff0000, v16
	v_pk_mul_f32 v[92:93], v[92:93], v[252:253]
	v_lshlrev_b32_e32 v178, 16, v17
	v_and_b32_e32 v179, 0xffff0000, v17
	v_pk_mul_f32 v[94:95], v[94:95], v[178:179]
	v_lshlrev_b32_e32 v244, 16, v18
	v_and_b32_e32 v245, 0xffff0000, v18
	v_pk_mul_f32 v[88:89], v[88:89], v[244:245]
	v_lshlrev_b32_e32 v246, 16, v19
	v_and_b32_e32 v247, 0xffff0000, v19
	v_pk_mul_f32 v[90:91], v[90:91], v[246:247]
	v_lshlrev_b32_e32 v252, 16, v32
	v_and_b32_e32 v253, 0xffff0000, v32
	v_pk_add_f32 v[92:93], v[92:93], v[252:253]
	v_lshlrev_b32_e32 v178, 16, v33
	v_and_b32_e32 v179, 0xffff0000, v33
	v_pk_add_f32 v[94:95], v[94:95], v[178:179]
	v_lshlrev_b32_e32 v244, 16, v34
	v_and_b32_e32 v245, 0xffff0000, v34
	v_pk_add_f32 v[88:89], v[88:89], v[244:245]
	v_lshlrev_b32_e32 v246, 16, v35
	v_and_b32_e32 v247, 0xffff0000, v35
	v_pk_add_f32 v[90:91], v[90:91], v[246:247]
	v_cvt_pk_bf16_f32 v16, v92, v93
	v_cvt_pk_bf16_f32 v17, v94, v95
	v_cvt_pk_bf16_f32 v18, v88, v89
	v_cvt_pk_bf16_f32 v19, v90, v91
	s_mov_b32 s58, 0x18000
	v_lshl_add_u64 v[252:253], v[172:173], 0, s[58:59]
	global_store_dwordx4 v[252:253], v[16:19], off sc1
	s_waitcnt vmcnt(23)
	v_lshlrev_b32_e32 v178, 16, v24
	v_and_b32_e32 v179, 0xffff0000, v24
	v_pk_mul_f32 v[84:85], v[84:85], v[178:179]
	v_lshlrev_b32_e32 v244, 16, v25
	v_and_b32_e32 v245, 0xffff0000, v25
	v_pk_mul_f32 v[86:87], v[86:87], v[244:245]
	v_lshlrev_b32_e32 v246, 16, v26
	v_and_b32_e32 v247, 0xffff0000, v26
	v_pk_mul_f32 v[80:81], v[80:81], v[246:247]
	v_lshlrev_b32_e32 v252, 16, v27
	v_and_b32_e32 v253, 0xffff0000, v27
	v_pk_mul_f32 v[82:83], v[82:83], v[252:253]
	v_lshlrev_b32_e32 v178, 16, v44
	v_and_b32_e32 v179, 0xffff0000, v44
	v_pk_add_f32 v[84:85], v[84:85], v[178:179]
	v_lshlrev_b32_e32 v244, 16, v45
	v_and_b32_e32 v245, 0xffff0000, v45
	v_pk_add_f32 v[86:87], v[86:87], v[244:245]
	v_lshlrev_b32_e32 v246, 16, v46
	v_and_b32_e32 v247, 0xffff0000, v46
	v_pk_add_f32 v[80:81], v[80:81], v[246:247]
	v_lshlrev_b32_e32 v252, 16, v47
	v_and_b32_e32 v253, 0xffff0000, v47
	v_pk_add_f32 v[82:83], v[82:83], v[252:253]
	v_cvt_pk_bf16_f32 v24, v84, v85
	v_cvt_pk_bf16_f32 v25, v86, v87
	v_cvt_pk_bf16_f32 v26, v80, v81
	v_cvt_pk_bf16_f32 v27, v82, v83
	s_mov_b32 s58, 0x18000
	v_lshl_add_u64 v[178:179], v[172:173], 0, s[58:59]
	global_store_dwordx4 v[178:179], v[24:27], off offset:256 sc1
	s_waitcnt vmcnt(21)
	v_lshlrev_b32_e32 v244, 16, v136
	v_and_b32_e32 v245, 0xffff0000, v136
	v_pk_mul_f32 v[76:77], v[76:77], v[244:245]
	v_lshlrev_b32_e32 v246, 16, v137
	v_and_b32_e32 v247, 0xffff0000, v137
	v_pk_mul_f32 v[78:79], v[78:79], v[246:247]
	v_lshlrev_b32_e32 v252, 16, v138
	v_and_b32_e32 v253, 0xffff0000, v138
	v_pk_mul_f32 v[72:73], v[72:73], v[252:253]
	v_lshlrev_b32_e32 v178, 16, v139
	v_and_b32_e32 v179, 0xffff0000, v139
	v_pk_mul_f32 v[74:75], v[74:75], v[178:179]
	v_lshlrev_b32_e32 v244, 16, v152
	v_and_b32_e32 v245, 0xffff0000, v152
	v_pk_add_f32 v[76:77], v[76:77], v[244:245]
	v_lshlrev_b32_e32 v246, 16, v153
	v_and_b32_e32 v247, 0xffff0000, v153
	v_pk_add_f32 v[78:79], v[78:79], v[246:247]
	v_lshlrev_b32_e32 v252, 16, v154
	v_and_b32_e32 v253, 0xffff0000, v154
	v_pk_add_f32 v[72:73], v[72:73], v[252:253]
	v_lshlrev_b32_e32 v178, 16, v155
	v_and_b32_e32 v179, 0xffff0000, v155
	v_pk_add_f32 v[74:75], v[74:75], v[178:179]
	v_cvt_pk_bf16_f32 v136, v76, v77
	v_cvt_pk_bf16_f32 v137, v78, v79
	v_cvt_pk_bf16_f32 v138, v72, v73
	v_cvt_pk_bf16_f32 v139, v74, v75
	s_mov_b32 s58, 0x40000
	v_lshl_add_u64 v[244:245], v[172:173], 0, s[58:59]
	global_store_dwordx4 v[244:245], v[136:139], off sc1
	s_waitcnt vmcnt(21)
	v_lshlrev_b32_e32 v246, 16, v148
	v_and_b32_e32 v247, 0xffff0000, v148
	v_pk_mul_f32 v[68:69], v[68:69], v[246:247]
	v_lshlrev_b32_e32 v252, 16, v149
	v_and_b32_e32 v253, 0xffff0000, v149
	v_pk_mul_f32 v[70:71], v[70:71], v[252:253]
	v_lshlrev_b32_e32 v178, 16, v150
	v_and_b32_e32 v179, 0xffff0000, v150
	v_pk_mul_f32 v[64:65], v[64:65], v[178:179]
	v_lshlrev_b32_e32 v244, 16, v151
	v_and_b32_e32 v245, 0xffff0000, v151
	v_pk_mul_f32 v[66:67], v[66:67], v[244:245]
	v_lshlrev_b32_e32 v246, 16, v156
	v_and_b32_e32 v247, 0xffff0000, v156
	v_pk_add_f32 v[68:69], v[68:69], v[246:247]
	v_lshlrev_b32_e32 v252, 16, v157
	v_and_b32_e32 v253, 0xffff0000, v157
	v_pk_add_f32 v[70:71], v[70:71], v[252:253]
	v_lshlrev_b32_e32 v178, 16, v158
	v_and_b32_e32 v179, 0xffff0000, v158
	v_pk_add_f32 v[64:65], v[64:65], v[178:179]
	v_lshlrev_b32_e32 v244, 16, v159
	v_and_b32_e32 v245, 0xffff0000, v159
	v_pk_add_f32 v[66:67], v[66:67], v[244:245]
	v_cvt_pk_bf16_f32 v148, v68, v69
	v_cvt_pk_bf16_f32 v149, v70, v71
	v_cvt_pk_bf16_f32 v150, v64, v65
	v_cvt_pk_bf16_f32 v151, v66, v67
	s_mov_b32 s58, 0x40000
	v_lshl_add_u64 v[246:247], v[172:173], 0, s[58:59]
	global_store_dwordx4 v[246:247], v[148:151], off offset:256 sc1
	s_waitcnt vmcnt(17)
	v_lshlrev_b32_e32 v252, 16, v140
	v_and_b32_e32 v253, 0xffff0000, v140
	v_pk_mul_f32 v[60:61], v[60:61], v[252:253]
	v_lshlrev_b32_e32 v178, 16, v141
	v_and_b32_e32 v179, 0xffff0000, v141
	v_pk_mul_f32 v[62:63], v[62:63], v[178:179]
	v_lshlrev_b32_e32 v244, 16, v142
	v_and_b32_e32 v245, 0xffff0000, v142
	v_pk_mul_f32 v[56:57], v[56:57], v[244:245]
	v_lshlrev_b32_e32 v246, 16, v143
	v_and_b32_e32 v247, 0xffff0000, v143
	v_pk_mul_f32 v[58:59], v[58:59], v[246:247]
	v_lshlrev_b32_e32 v252, 16, v180
	v_and_b32_e32 v253, 0xffff0000, v180
	v_pk_add_f32 v[60:61], v[60:61], v[252:253]
	v_lshlrev_b32_e32 v178, 16, v181
	v_and_b32_e32 v179, 0xffff0000, v181
	v_pk_add_f32 v[62:63], v[62:63], v[178:179]
	v_lshlrev_b32_e32 v244, 16, v182
	v_and_b32_e32 v245, 0xffff0000, v182
	v_pk_add_f32 v[56:57], v[56:57], v[244:245]
	v_lshlrev_b32_e32 v246, 16, v183
	v_and_b32_e32 v247, 0xffff0000, v183
	v_pk_add_f32 v[58:59], v[58:59], v[246:247]
	v_cvt_pk_bf16_f32 v140, v60, v61
	v_cvt_pk_bf16_f32 v141, v62, v63
	v_cvt_pk_bf16_f32 v142, v56, v57
	v_cvt_pk_bf16_f32 v143, v58, v59
	s_mov_b32 s58, 0x48000
	v_lshl_add_u64 v[252:253], v[172:173], 0, s[58:59]
	global_store_dwordx4 v[252:253], v[140:143], off sc1
	s_waitcnt vmcnt(17)
	v_lshlrev_b32_e32 v178, 16, v144
	v_and_b32_e32 v179, 0xffff0000, v144
	v_pk_mul_f32 v[52:53], v[52:53], v[178:179]
	v_lshlrev_b32_e32 v244, 16, v145
	v_and_b32_e32 v245, 0xffff0000, v145
	v_pk_mul_f32 v[54:55], v[54:55], v[244:245]
	v_lshlrev_b32_e32 v246, 16, v146
	v_and_b32_e32 v247, 0xffff0000, v146
	v_pk_mul_f32 v[48:49], v[48:49], v[246:247]
	v_lshlrev_b32_e32 v252, 16, v147
	v_and_b32_e32 v253, 0xffff0000, v147
	v_pk_mul_f32 v[50:51], v[50:51], v[252:253]
	v_lshlrev_b32_e32 v178, 16, v188
	v_and_b32_e32 v179, 0xffff0000, v188
	v_pk_add_f32 v[52:53], v[52:53], v[178:179]
	v_lshlrev_b32_e32 v244, 16, v189
	v_and_b32_e32 v245, 0xffff0000, v189
	v_pk_add_f32 v[54:55], v[54:55], v[244:245]
	v_lshlrev_b32_e32 v246, 16, v190
	v_and_b32_e32 v247, 0xffff0000, v190
	v_pk_add_f32 v[48:49], v[48:49], v[246:247]
	v_lshlrev_b32_e32 v252, 16, v191
	v_and_b32_e32 v253, 0xffff0000, v191
	v_pk_add_f32 v[50:51], v[50:51], v[252:253]
	v_cvt_pk_bf16_f32 v144, v52, v53
	v_cvt_pk_bf16_f32 v145, v54, v55
	v_cvt_pk_bf16_f32 v146, v48, v49
	v_cvt_pk_bf16_f32 v147, v50, v51
	s_mov_b32 s58, 0x48000
	v_lshl_add_u64 v[178:179], v[172:173], 0, s[58:59]
	global_store_dwordx4 v[178:179], v[144:147], off offset:256 sc1
	s_waitcnt vmcnt(15)
	v_lshlrev_b32_e32 v244, 16, v128
	v_and_b32_e32 v245, 0xffff0000, v128
	v_pk_mul_f32 v[40:41], v[40:41], v[244:245]
	v_lshlrev_b32_e32 v246, 16, v129
	v_and_b32_e32 v247, 0xffff0000, v129
	v_pk_mul_f32 v[42:43], v[42:43], v[246:247]
	v_lshlrev_b32_e32 v252, 16, v130
	v_and_b32_e32 v253, 0xffff0000, v130
	v_pk_mul_f32 v[36:37], v[36:37], v[252:253]
	v_lshlrev_b32_e32 v178, 16, v131
	v_and_b32_e32 v179, 0xffff0000, v131
	v_pk_mul_f32 v[38:39], v[38:39], v[178:179]
	v_lshlrev_b32_e32 v244, 16, v184
	v_and_b32_e32 v245, 0xffff0000, v184
	v_pk_add_f32 v[40:41], v[40:41], v[244:245]
	v_lshlrev_b32_e32 v246, 16, v185
	v_and_b32_e32 v247, 0xffff0000, v185
	v_pk_add_f32 v[42:43], v[42:43], v[246:247]
	v_lshlrev_b32_e32 v252, 16, v186
	v_and_b32_e32 v253, 0xffff0000, v186
	v_pk_add_f32 v[36:37], v[36:37], v[252:253]
	v_lshlrev_b32_e32 v178, 16, v187
	v_and_b32_e32 v179, 0xffff0000, v187
	v_pk_add_f32 v[38:39], v[38:39], v[178:179]
	v_cvt_pk_bf16_f32 v128, v40, v41
	v_cvt_pk_bf16_f32 v129, v42, v43
	v_cvt_pk_bf16_f32 v130, v36, v37
	v_cvt_pk_bf16_f32 v131, v38, v39
	s_mov_b32 s58, 0x50000
	v_lshl_add_u64 v[244:245], v[172:173], 0, s[58:59]
	global_store_dwordx4 v[244:245], v[128:131], off sc1
	s_waitcnt vmcnt(15)
	v_lshlrev_b32_e32 v246, 16, v132
	v_and_b32_e32 v247, 0xffff0000, v132
	v_pk_mul_f32 v[28:29], v[28:29], v[246:247]
	v_lshlrev_b32_e32 v252, 16, v133
	v_and_b32_e32 v253, 0xffff0000, v133
	v_pk_mul_f32 v[30:31], v[30:31], v[252:253]
	v_lshlrev_b32_e32 v178, 16, v134
	v_and_b32_e32 v179, 0xffff0000, v134
	v_pk_mul_f32 v[20:21], v[20:21], v[178:179]
	v_lshlrev_b32_e32 v244, 16, v135
	v_and_b32_e32 v245, 0xffff0000, v135
	v_pk_mul_f32 v[22:23], v[22:23], v[244:245]
	v_lshlrev_b32_e32 v246, 16, v192
	v_and_b32_e32 v247, 0xffff0000, v192
	v_pk_add_f32 v[28:29], v[28:29], v[246:247]
	v_lshlrev_b32_e32 v252, 16, v193
	v_and_b32_e32 v253, 0xffff0000, v193
	v_pk_add_f32 v[30:31], v[30:31], v[252:253]
	v_lshlrev_b32_e32 v178, 16, v194
	v_and_b32_e32 v179, 0xffff0000, v194
	v_pk_add_f32 v[20:21], v[20:21], v[178:179]
	v_lshlrev_b32_e32 v244, 16, v195
	v_and_b32_e32 v245, 0xffff0000, v195
	v_pk_add_f32 v[22:23], v[22:23], v[244:245]
	v_cvt_pk_bf16_f32 v132, v28, v29
	v_cvt_pk_bf16_f32 v133, v30, v31
	v_cvt_pk_bf16_f32 v134, v20, v21
	v_cvt_pk_bf16_f32 v135, v22, v23
	s_mov_b32 s58, 0x50000
	v_lshl_add_u64 v[246:247], v[172:173], 0, s[58:59]
	global_store_dwordx4 v[246:247], v[132:135], off offset:256 sc1
	s_waitcnt vmcnt(11)
	v_lshlrev_b32_e32 v252, 16, v120
	v_and_b32_e32 v253, 0xffff0000, v120
	v_pk_mul_f32 v[12:13], v[12:13], v[252:253]
	v_lshlrev_b32_e32 v178, 16, v121
	v_and_b32_e32 v179, 0xffff0000, v121
	v_pk_mul_f32 v[14:15], v[14:15], v[178:179]
	v_lshlrev_b32_e32 v244, 16, v122
	v_and_b32_e32 v245, 0xffff0000, v122
	v_pk_mul_f32 v[8:9], v[8:9], v[244:245]
	v_lshlrev_b32_e32 v246, 16, v123
	v_and_b32_e32 v247, 0xffff0000, v123
	v_pk_mul_f32 v[10:11], v[10:11], v[246:247]
	v_lshlrev_b32_e32 v252, 16, v196
	v_and_b32_e32 v253, 0xffff0000, v196
	v_pk_add_f32 v[12:13], v[12:13], v[252:253]
	v_lshlrev_b32_e32 v178, 16, v197
	v_and_b32_e32 v179, 0xffff0000, v197
	v_pk_add_f32 v[14:15], v[14:15], v[178:179]
	v_lshlrev_b32_e32 v244, 16, v198
	v_and_b32_e32 v245, 0xffff0000, v198
	v_pk_add_f32 v[8:9], v[8:9], v[244:245]
	v_lshlrev_b32_e32 v246, 16, v199
	v_and_b32_e32 v247, 0xffff0000, v199
	v_pk_add_f32 v[10:11], v[10:11], v[246:247]
	v_cvt_pk_bf16_f32 v120, v12, v13
	v_cvt_pk_bf16_f32 v121, v14, v15
	v_cvt_pk_bf16_f32 v122, v8, v9
	v_cvt_pk_bf16_f32 v123, v10, v11
	s_mov_b32 s58, 0x58000
	v_lshl_add_u64 v[252:253], v[172:173], 0, s[58:59]
	global_store_dwordx4 v[252:253], v[120:123], off sc1
	s_waitcnt vmcnt(11)
	v_lshlrev_b32_e32 v178, 16, v124
	v_and_b32_e32 v179, 0xffff0000, v124
	v_pk_mul_f32 v[4:5], v[4:5], v[178:179]
	v_lshlrev_b32_e32 v244, 16, v125
	v_and_b32_e32 v245, 0xffff0000, v125
	v_pk_mul_f32 v[6:7], v[6:7], v[244:245]
	v_lshlrev_b32_e32 v246, 16, v126
	v_and_b32_e32 v247, 0xffff0000, v126
	v_pk_mul_f32 v[0:1], v[0:1], v[246:247]
	v_lshlrev_b32_e32 v252, 16, v127
	v_and_b32_e32 v253, 0xffff0000, v127
	v_pk_mul_f32 v[2:3], v[2:3], v[252:253]
	v_lshlrev_b32_e32 v178, 16, v204
	v_and_b32_e32 v179, 0xffff0000, v204
	v_pk_add_f32 v[4:5], v[4:5], v[178:179]
	v_lshlrev_b32_e32 v244, 16, v205
	v_and_b32_e32 v245, 0xffff0000, v205
	v_pk_add_f32 v[6:7], v[6:7], v[244:245]
	v_lshlrev_b32_e32 v246, 16, v206
	v_and_b32_e32 v247, 0xffff0000, v206
	v_pk_add_f32 v[0:1], v[0:1], v[246:247]
	v_lshlrev_b32_e32 v252, 16, v207
	v_and_b32_e32 v253, 0xffff0000, v207
	v_pk_add_f32 v[2:3], v[2:3], v[252:253]
	v_cvt_pk_bf16_f32 v124, v4, v5
	v_cvt_pk_bf16_f32 v125, v6, v7
	v_cvt_pk_bf16_f32 v126, v0, v1
	v_cvt_pk_bf16_f32 v127, v2, v3
	s_mov_b32 s58, 0x58000
	v_lshl_add_u64 v[178:179], v[172:173], 0, s[58:59]
	global_store_dwordx4 v[178:179], v[124:127], off offset:256 sc1
	s_branch .Lmepi_done
